# baseline (speedup 1.0000x reference)
; __device__ __forceinline__ unsigned cvtpk(float lo, float hi) { unsigned r; asm volatile("v_cvt_pk_bf16_f32 %0, %1, %2" : "=v"(r) : "v"(lo), "v"(hi)); return r; }
; __device__ __forceinline__ float bflo(unsigned w) { return __uint_as_float(w << 16); }
; __device__ __forceinline__ float bfhi(unsigned w) { return __uint_as_float(w & 0xffff0000u); }
; __device__ __forceinline__ float fexp(float x) { return __builtin_amdgcn_exp2f(x * 1.4426950408889634f); }
; __device__ __forceinline__ int v_st(int k, int c) { const int kk = (k & ~0xC) | ((k & 4) << 1) | ((k & 8) >> 1); return ((kk >> 3) * 4 + (c >> 5)) * 512 + ((kk & 7) * 32 + (c & 31)) * 2; }
; __device__ __forceinline__ void mlstm_item(const int tid0, const P& p, int item, char* lds) {
;     ...
;         const float U = pU, bL = pbL;
;         const float Mlast = fmaxf(m, U);
; #pragma unroll
;         for (int i = 0; i < 4; ++i) {
;             const int piece = tid + NTHR * i, s = piece >> 4, cc = (piece & 15) * 8;
;             const u32x4 kv = pk[i], vv = pv[i];
;             const float wsv = fexp(pgu[i] - Mlast);
;             *(u32x4*)(Ks + KSWZ(s, cc * 2)) = kv;
;             u32x4 ks; ks.x = cvtpk(bflo(kv.x) * wsv, bfhi(kv.x) * wsv); ks.y = cvtpk(bflo(kv.y) * wsv, bfhi(kv.y) * wsv);
;             ks.z = cvtpk(bflo(kv.z) * wsv, bfhi(kv.z) * wsv); ks.w = cvtpk(bflo(kv.w) * wsv, bfhi(kv.w) * wsv);
;             const int so = (s >> 6) * 16384 + v_st(s & 63, cc);
;             *(u32x4*)(Kt + so) = ks; *(u32x4*)(Vt + so) = vv;
;         }
;         __syncthreads();
.LBB0_167:
	s_or_b64 exec, exec, s[8:9]
	s_waitcnt vmcnt(9)
	v_max_f32_e32 v50, v189, v189
	v_max_f32_e32 v112, v193, v193
	v_max_f32_e32 v190, v112, v50
	v_lshlrev_b32_e32 v50, 3, v196
	v_and_b32_e32 v51, 0x78, v50
	v_bfe_u32 v55, v50, 5, 2
	v_sub_f32_e32 v50, v179, v190
	v_mul_f32_e32 v50, 0x3fb8aa3b, v50
	v_lshlrev_b32_e32 v178, 1, v51
	v_and_b32_e32 v51, 0x70, v196
	v_exp_f32_e32 v53, v50
	v_xad_u32 v54, v178, v51, 0
	v_ashrrev_i32_e32 v197, 4, v196
	v_lshl_add_u32 v50, v197, 8, v54
	ds_write_b128 v50, v[114:117]
	v_lshlrev_b32_e32 v50, 16, v114
	v_and_b32_e32 v51, 0xffff0000, v114
	v_mul_f32_e32 v50, v53, v50
	v_mul_f32_e32 v51, v53, v51
	v_cvt_pk_bf16_f32 v50, v50, v51
	v_lshlrev_b32_e32 v51, 16, v115
	v_and_b32_e32 v52, 0xffff0000, v115
	v_mul_f32_e32 v51, v53, v51
	v_mul_f32_e32 v52, v53, v52
	v_cvt_pk_bf16_f32 v51, v51, v52
	v_lshlrev_b32_e32 v52, 16, v116
	v_and_b32_e32 v57, 0xffff0000, v116
	v_mul_f32_e32 v52, v53, v52
	v_mul_f32_e32 v57, v53, v57
	v_and_b32_e32 v59, 48, v197
	v_lshlrev_b32_e32 v60, 1, v197
	v_cvt_pk_bf16_f32 v52, v52, v57
	v_lshlrev_b32_e32 v57, 16, v117
	v_and_b32_e32 v58, 0xffff0000, v117
	v_and_or_b32 v59, v60, 8, v59
	v_lshrrev_b32_e32 v60, 1, v197
	v_and_b32_e32 v61, 3, v197
	v_mul_f32_e32 v57, v53, v57
	v_mul_f32_e32 v53, v53, v58
	v_lshrrev_b32_e32 v59, 1, v59
	v_and_or_b32 v60, v60, 4, v61
	v_cvt_pk_bf16_f32 v53, v57, v53
	v_lshlrev_b32_e32 v57, 4, v196
	v_or_b32_e32 v59, v59, v55
	v_lshlrev_b32_e32 v60, 6, v60
	v_and_b32_e32 v56, 48, v178
	v_and_b32_e32 v58, 0xffffc000, v57
	v_lshl_or_b32 v59, v59, 9, v60
	v_or3_b32 v58, v59, v58, v56
	v_add_u32_e32 v59, s57, v58
	ds_write_b128 v59, v[50:53]
	v_add_u32_e32 v50, 0, v58
	ds_write_b128 v50, v[118:121] offset:32768
	v_sub_f32_e32 v50, v182, v190
	v_mul_f32_e32 v50, 0x3fb8aa3b, v50
	v_add_u32_e32 v58, 0x200, v196
	v_exp_f32_e32 v53, v50
	v_ashrrev_i32_e32 v198, 4, v58
	v_lshl_add_u32 v50, v198, 8, v54
	ds_write_b128 v50, v[122:125]
	v_lshlrev_b32_e32 v50, 16, v122
	v_and_b32_e32 v51, 0xffff0000, v122
	v_mul_f32_e32 v50, v53, v50
	v_mul_f32_e32 v51, v53, v51
	v_cvt_pk_bf16_f32 v50, v50, v51
	v_lshlrev_b32_e32 v51, 16, v123
	v_and_b32_e32 v52, 0xffff0000, v123
	v_mul_f32_e32 v51, v53, v51
	v_mul_f32_e32 v52, v53, v52
	v_cvt_pk_bf16_f32 v51, v51, v52
	v_lshlrev_b32_e32 v52, 16, v124
	v_and_b32_e32 v59, 0xffff0000, v124
	v_mul_f32_e32 v52, v53, v52
	v_mul_f32_e32 v59, v53, v59
	v_cvt_pk_bf16_f32 v52, v52, v59
	v_lshlrev_b32_e32 v59, 16, v125
	v_and_b32_e32 v60, 0xffff0000, v125
	v_mul_f32_e32 v59, v53, v59
	v_mul_f32_e32 v53, v53, v60
	v_cvt_pk_bf16_f32 v53, v59, v53
	v_and_b32_e32 v59, 48, v198
	v_lshlrev_b32_e32 v60, 1, v198
	v_and_or_b32 v59, v60, 8, v59
	v_lshrrev_b32_e32 v60, 1, v198
	v_and_b32_e32 v61, 3, v198
	v_lshrrev_b32_e32 v59, 1, v59
	v_and_or_b32 v60, v60, 4, v61
	v_lshlrev_b32_e32 v58, 4, v58
	v_or_b32_e32 v59, v59, v55
	v_lshlrev_b32_e32 v60, 6, v60
	v_and_b32_e32 v58, 0xffffc000, v58
	v_lshl_or_b32 v59, v59, 9, v60
	v_or3_b32 v58, v59, v58, v56
	v_add_u32_e32 v59, s57, v58
	ds_write_b128 v59, v[50:53]
	v_add_u32_e32 v50, 0, v58
	ds_write_b128 v50, v[126:129] offset:32768
	v_sub_f32_e32 v50, v186, v190
	v_mul_f32_e32 v50, 0x3fb8aa3b, v50
	v_add_u32_e32 v58, 0x400, v196
	v_exp_f32_e32 v53, v50
	v_ashrrev_i32_e32 v199, 4, v58
	v_lshl_add_u32 v50, v199, 8, v54
	ds_write_b128 v50, v[130:133]
	v_lshlrev_b32_e32 v50, 16, v130
	v_and_b32_e32 v51, 0xffff0000, v130
	v_mul_f32_e32 v50, v53, v50
	v_mul_f32_e32 v51, v53, v51
	v_cvt_pk_bf16_f32 v50, v50, v51
	v_lshlrev_b32_e32 v51, 16, v131
	v_and_b32_e32 v52, 0xffff0000, v131
	v_mul_f32_e32 v51, v53, v51
	v_mul_f32_e32 v52, v53, v52
	v_cvt_pk_bf16_f32 v51, v51, v52
	v_lshlrev_b32_e32 v52, 16, v132
	v_and_b32_e32 v59, 0xffff0000, v132
	v_mul_f32_e32 v52, v53, v52
	v_mul_f32_e32 v59, v53, v59
	v_cvt_pk_bf16_f32 v52, v52, v59
	v_lshlrev_b32_e32 v59, 16, v133
	v_and_b32_e32 v60, 0xffff0000, v133
	v_mul_f32_e32 v59, v53, v59
	v_mul_f32_e32 v53, v53, v60
	v_cvt_pk_bf16_f32 v53, v59, v53
	v_and_b32_e32 v59, 48, v199
	v_lshlrev_b32_e32 v60, 1, v199
	v_and_or_b32 v59, v60, 8, v59
	v_lshrrev_b32_e32 v60, 1, v199
	v_and_b32_e32 v61, 3, v199
	v_lshrrev_b32_e32 v59, 1, v59
	v_and_or_b32 v60, v60, 4, v61
	v_lshlrev_b32_e32 v58, 4, v58
	v_or_b32_e32 v59, v59, v55
	v_lshlrev_b32_e32 v60, 6, v60
	v_and_b32_e32 v58, 0xffffc000, v58
	v_lshl_or_b32 v59, v59, 9, v60
	v_or3_b32 v58, v59, v58, v56
	v_add_u32_e32 v59, s57, v58
	ds_write_b128 v59, v[50:53]
	v_add_u32_e32 v50, 0, v58
	ds_write_b128 v50, v[134:137] offset:32768
	v_sub_f32_e32 v50, v187, v190
	v_mul_f32_e32 v50, 0x3fb8aa3b, v50
	v_add_u32_e32 v58, 0x600, v196
	v_exp_f32_e32 v53, v50
	v_ashrrev_i32_e32 v200, 4, v58
	v_lshl_add_u32 v50, v200, 8, v54
	ds_write_b128 v50, v[138:141]
	v_lshlrev_b32_e32 v50, 16, v138
	v_and_b32_e32 v51, 0xffff0000, v138
	v_mul_f32_e32 v50, v53, v50
	v_mul_f32_e32 v51, v53, v51
	v_cvt_pk_bf16_f32 v50, v50, v51
	v_lshlrev_b32_e32 v51, 16, v139
	v_and_b32_e32 v52, 0xffff0000, v139
	v_mul_f32_e32 v51, v53, v51
	v_mul_f32_e32 v52, v53, v52
	v_cvt_pk_bf16_f32 v51, v51, v52
	v_lshlrev_b32_e32 v52, 16, v140
	v_and_b32_e32 v54, 0xffff0000, v140
	v_mul_f32_e32 v52, v53, v52
	v_mul_f32_e32 v54, v53, v54
	v_cvt_pk_bf16_f32 v52, v52, v54
	v_lshlrev_b32_e32 v54, 16, v141
	v_and_b32_e32 v59, 0xffff0000, v141
	v_mul_f32_e32 v54, v53, v54
	v_mul_f32_e32 v53, v53, v59
	v_cvt_pk_bf16_f32 v53, v54, v53
	v_lshlrev_b32_e32 v54, 4, v58
	v_and_b32_e32 v58, 48, v200
	v_lshlrev_b32_e32 v59, 1, v200
	v_and_or_b32 v58, v59, 8, v58
	v_lshrrev_b32_e32 v58, 1, v58
	v_lshrrev_b32_e32 v59, 1, v200
	v_or_b32_e32 v55, v58, v55
	v_and_b32_e32 v58, 3, v200
	v_and_or_b32 v58, v59, 4, v58
	v_lshlrev_b32_e32 v58, 6, v58
	v_and_b32_e32 v54, 0xffffc000, v54
	v_lshl_or_b32 v55, v55, 9, v58
	v_or3_b32 v54, v55, v54, v56
	v_lshlrev_b32_e32 v113, 8, v191
	v_add_u32_e32 v55, s57, v54
	v_and_b32_e32 v194, 0x70, v57
	v_add_u32_e32 v195, s49, v113
	ds_write_b128 v55, v[50:53]
	v_add_u32_e32 v50, 0, v54
	v_xad_u32 v54, v0, v194, v195
	ds_write_b128 v50, v[142:145] offset:32768
	s_waitcnt lgkmcnt(0)
	s_barrier
; __device__ __forceinline__ float bf2f(short x) { return __uint_as_float(((unsigned)(unsigned short)x) << 16); }
; __device__ __forceinline__ void mlstm_item(const int tid0, const P& p, int item, char* lds) {
;     ...
;         for (int d0 = 0; d0 < 8; ++d0) { const int cb = (d0 * 16 + hi * 8) * 2;
;             const bf16x8 c0 = *reinterpret_cast<const bf16x8*>(Cs + KSWZ(64 * vh + r32, cb));
;             const bf16x8 c1 = *reinterpret_cast<const bf16x8*>(Cs + KSWZ(64 * vh + 32 + r32, cb));
;             o0 = __builtin_amdgcn_mfma_f32_32x32x16_bf16(qr[d0], c0, o0, 0, 0, 0);
;             o1 = __builtin_amdgcn_mfma_f32_32x32x16_bf16(qr[d0], c1, o1, 0, 0, 0); }
;         float nq = 0.f;
; #pragma unroll
;         for (int d0 = 0; d0 < 8; ++d0)
; #pragma unroll
;             for (int i = 0; i < 8; ++i) nq += bf2f(qr[d0][i]) * nvec[16 * d0 + 8 * hi + i];
	ds_read_b128 v[50:53], v54
	ds_read_b128 v[66:69], v54 offset:8192
	s_waitcnt vmcnt(7) lgkmcnt(1)
	v_mfma_f32_32x32x16_bf16 v[50:65], v[174:177], v[50:53], 0
	v_or_b32_e32 v180, 32, v0
	v_xad_u32 v74, v180, v194, v195
	ds_read_b128 v[70:73], v74
	ds_read_b128 v[106:109], v74 offset:8192
	v_or_b32_e32 v181, 64, v0
	v_xad_u32 v74, v181, v194, v195
	v_or_b32_e32 v211, 0x60, v0
	v_or_b32_e32 v213, 0x80, v0
	s_waitcnt vmcnt(6) lgkmcnt(1)
	v_mfma_f32_32x32x16_bf16 v[50:65], v[170:173], v[70:73], v[50:65]
	ds_read_b128 v[70:73], v74
	ds_read_b128 v[102:105], v74 offset:8192
	v_xad_u32 v74, v211, v194, v195
	v_or_b32_e32 v214, 0xa0, v0
	v_or_b32_e32 v215, 0xc0, v0
	v_or_b32_e32 v216, 0xe0, v0
	v_lshlrev_b32_e32 v192, 3, v110
	v_lshl_add_u32 v206, v201, 2, 0
	s_waitcnt vmcnt(5) lgkmcnt(1)
	v_mfma_f32_32x32x16_bf16 v[50:65], v[166:169], v[70:73], v[50:65]
	ds_read_b128 v[70:73], v74
	ds_read_b128 v[98:101], v74 offset:8192
	v_xad_u32 v74, v213, v194, v195
	v_and_b32_e32 v111, 63, v196
	v_cmp_gt_u32_e64 s[8:9], 32, v111
	v_lshl_add_u32 v207, v191, 2, s38
	s_waitcnt vmcnt(4) lgkmcnt(1)
	v_mfma_f32_32x32x16_bf16 v[50:65], v[162:165], v[70:73], v[50:65]
	ds_read_b128 v[70:73], v74
	ds_read_b128 v[94:97], v74 offset:8192
	v_xad_u32 v74, v214, v194, v195
	s_waitcnt vmcnt(3) lgkmcnt(1)
	v_mfma_f32_32x32x16_bf16 v[50:65], v[158:161], v[70:73], v[50:65]
	ds_read_b128 v[70:73], v74
	ds_read_b128 v[90:93], v74 offset:8192
	v_xad_u32 v74, v215, v194, v195
	s_waitcnt vmcnt(2) lgkmcnt(1)
	v_mfma_f32_32x32x16_bf16 v[50:65], v[154:157], v[70:73], v[50:65]
	ds_read_b128 v[70:73], v74
	ds_read_b128 v[82:85], v74 offset:8192
	v_xad_u32 v74, v216, v194, v195
	s_waitcnt vmcnt(1) lgkmcnt(1)
	v_mfma_f32_32x32x16_bf16 v[50:65], v[150:153], v[70:73], v[50:65]
	ds_read_b128 v[70:73], v74
	ds_read_b128 v[86:89], v74 offset:8192
	s_waitcnt vmcnt(0) lgkmcnt(1)
	v_mfma_f32_32x32x16_bf16 v[50:65], v[146:149], v[70:73], v[50:65]
	v_lshl_add_u32 v70, v192, 2, 0
	v_add_u32_e32 v70, 0x20600, v70
	ds_read_b128 v[116:119], v70 offset:0
	ds_read_b128 v[120:123], v70 offset:16
	ds_read_b128 v[124:127], v70 offset:64
	ds_read_b128 v[128:131], v70 offset:80
	ds_read_b128 v[220:223], v70 offset:128
	ds_read_b128 v[224:227], v70 offset:144
	ds_read_b128 v[228:231], v70 offset:192
	ds_read_b128 v[232:235], v70 offset:208
	s_waitcnt lgkmcnt(7)
	v_lshlrev_b32_e32 v71, 16, v174
	v_fma_f32 v202, v116, v71, 0
	v_and_b32_e32 v71, 0xffff0000, v174
	v_fmac_f32_e32 v202, v117, v71
	v_lshlrev_b32_e32 v71, 16, v175
	v_fmac_f32_e32 v202, v118, v71
	v_and_b32_e32 v71, 0xffff0000, v175
	v_fmac_f32_e32 v202, v119, v71
	ds_read_b128 v[116:119], v70 offset:256
	s_waitcnt lgkmcnt(7)
	v_lshlrev_b32_e32 v71, 16, v176
	v_fmac_f32_e32 v202, v120, v71
	v_and_b32_e32 v71, 0xffff0000, v176
	v_fmac_f32_e32 v202, v121, v71
	v_lshlrev_b32_e32 v71, 16, v177
	v_fmac_f32_e32 v202, v122, v71
	v_and_b32_e32 v71, 0xffff0000, v177
	v_fmac_f32_e32 v202, v123, v71
	ds_read_b128 v[120:123], v70 offset:272
	s_waitcnt lgkmcnt(7)
	v_lshlrev_b32_e32 v71, 16, v170
	v_fmac_f32_e32 v202, v124, v71
	v_and_b32_e32 v71, 0xffff0000, v170
	v_fmac_f32_e32 v202, v125, v71
	v_lshlrev_b32_e32 v71, 16, v171
	v_fmac_f32_e32 v202, v126, v71
	v_and_b32_e32 v71, 0xffff0000, v171
	v_fmac_f32_e32 v202, v127, v71
	ds_read_b128 v[124:127], v70 offset:320
	s_waitcnt lgkmcnt(7)
	v_lshlrev_b32_e32 v71, 16, v172
	v_fmac_f32_e32 v202, v128, v71
	v_and_b32_e32 v71, 0xffff0000, v172
	v_fmac_f32_e32 v202, v129, v71
	v_lshlrev_b32_e32 v71, 16, v173
	v_fmac_f32_e32 v202, v130, v71
	v_and_b32_e32 v71, 0xffff0000, v173
	v_fmac_f32_e32 v202, v131, v71
	ds_read_b128 v[128:131], v70 offset:336
	s_waitcnt lgkmcnt(7)
	v_lshlrev_b32_e32 v71, 16, v166
	v_fmac_f32_e32 v202, v220, v71
	v_and_b32_e32 v71, 0xffff0000, v166
	v_fmac_f32_e32 v202, v221, v71
	v_lshlrev_b32_e32 v71, 16, v167
	v_fmac_f32_e32 v202, v222, v71
	v_and_b32_e32 v71, 0xffff0000, v167
	v_fmac_f32_e32 v202, v223, v71
	ds_read_b128 v[220:223], v70 offset:384
	s_waitcnt lgkmcnt(7)
	v_lshlrev_b32_e32 v71, 16, v168
	v_fmac_f32_e32 v202, v224, v71
	v_and_b32_e32 v71, 0xffff0000, v168
	v_fmac_f32_e32 v202, v225, v71
	v_lshlrev_b32_e32 v71, 16, v169
	v_fmac_f32_e32 v202, v226, v71
	v_and_b32_e32 v71, 0xffff0000, v169
	v_fmac_f32_e32 v202, v227, v71
	ds_read_b128 v[224:227], v70 offset:400
	s_waitcnt lgkmcnt(7)
	v_lshlrev_b32_e32 v71, 16, v162
	v_fmac_f32_e32 v202, v228, v71
	v_and_b32_e32 v71, 0xffff0000, v162
	v_fmac_f32_e32 v202, v229, v71
	v_lshlrev_b32_e32 v71, 16, v163
	v_fmac_f32_e32 v202, v230, v71
	v_and_b32_e32 v71, 0xffff0000, v163
	v_fmac_f32_e32 v202, v231, v71
	ds_read_b128 v[228:231], v70 offset:448
	s_waitcnt lgkmcnt(7)
	v_lshlrev_b32_e32 v71, 16, v164
	v_fmac_f32_e32 v202, v232, v71
	v_and_b32_e32 v71, 0xffff0000, v164
	v_fmac_f32_e32 v202, v233, v71
	v_lshlrev_b32_e32 v71, 16, v165
	v_fmac_f32_e32 v202, v234, v71
	v_and_b32_e32 v71, 0xffff0000, v165
	v_fmac_f32_e32 v202, v235, v71
	ds_read_b128 v[232:235], v70 offset:464
	s_waitcnt lgkmcnt(7)
	v_lshlrev_b32_e32 v71, 16, v158
	v_fmac_f32_e32 v202, v116, v71
	v_and_b32_e32 v71, 0xffff0000, v158
	v_fmac_f32_e32 v202, v117, v71
	v_lshlrev_b32_e32 v71, 16, v159
	v_fmac_f32_e32 v202, v118, v71
	v_and_b32_e32 v71, 0xffff0000, v159
	v_fmac_f32_e32 v202, v119, v71
	s_waitcnt lgkmcnt(6)
	v_lshlrev_b32_e32 v71, 16, v160
	v_fmac_f32_e32 v202, v120, v71
	v_and_b32_e32 v71, 0xffff0000, v160
	v_fmac_f32_e32 v202, v121, v71
	v_lshlrev_b32_e32 v71, 16, v161
	v_fmac_f32_e32 v202, v122, v71
	v_and_b32_e32 v71, 0xffff0000, v161
	v_fmac_f32_e32 v202, v123, v71
	s_waitcnt lgkmcnt(5)
; __device__ __forceinline__ float bf2f(short x) { return __uint_as_float(((unsigned)(unsigned short)x) << 16); }
; __device__ __forceinline__ float fexp(float x) { return __builtin_amdgcn_exp2f(x * 1.4426950408889634f); }
; __device__ __forceinline__ int crow(int r, int hi) { return (r & 3) + 8 * (r >> 2) + 4 * hi; }
; __device__ __forceinline__ void mlstm_item(const int tid0, const P& p, int item, char* lds) {
;     ...
;             for (int i = 0; i < 8; ++i) nq += bf2f(qr[d0][i]) * nvec[16 * d0 + 8 * hi + i];
;         nq = xadd<32>(nq);
;         const float Mt = fmaxf(m, scm[tl]), winter = fexp(m - Mt);
;         if (hi == 0) wsr[r32] = winter;
;         asm volatile("s_waitcnt lgkmcnt(0)" ::: "memory");
; #pragma unroll
;         for (int r = 0; r < 16; ++r) { const float f = wsr[crow(r, hi)]; o0[r] *= f; o1[r] *= f; }
;         float dsum = 0.f;
;         const float MtL = Mt * 1.4426950408889634f;
; #pragma unroll
;         for (int kt = 0; kt < 2; ++kt) {
;             if (dir ? (kt == 0 && w4 >= 2) : (kt == 1 && w4 < 2)) continue;
	v_lshlrev_b32_e32 v71, 16, v154
	v_fmac_f32_e32 v202, v124, v71
	v_and_b32_e32 v71, 0xffff0000, v154
	v_fmac_f32_e32 v202, v125, v71
	v_lshlrev_b32_e32 v71, 16, v155
	v_fmac_f32_e32 v202, v126, v71
	v_and_b32_e32 v71, 0xffff0000, v155
	v_fmac_f32_e32 v202, v127, v71
	s_waitcnt lgkmcnt(4)
	v_lshlrev_b32_e32 v71, 16, v156
	v_fmac_f32_e32 v202, v128, v71
	v_and_b32_e32 v71, 0xffff0000, v156
	v_fmac_f32_e32 v202, v129, v71
	v_lshlrev_b32_e32 v71, 16, v157
	v_fmac_f32_e32 v202, v130, v71
	v_and_b32_e32 v71, 0xffff0000, v157
	v_fmac_f32_e32 v202, v131, v71
	s_waitcnt lgkmcnt(3)
	v_lshlrev_b32_e32 v71, 16, v150
	v_fmac_f32_e32 v202, v220, v71
	v_and_b32_e32 v71, 0xffff0000, v150
	v_fmac_f32_e32 v202, v221, v71
	v_lshlrev_b32_e32 v71, 16, v151
	v_fmac_f32_e32 v202, v222, v71
	v_and_b32_e32 v71, 0xffff0000, v151
	v_fmac_f32_e32 v202, v223, v71
	s_waitcnt lgkmcnt(2)
	v_lshlrev_b32_e32 v71, 16, v152
	v_fmac_f32_e32 v202, v224, v71
	v_and_b32_e32 v71, 0xffff0000, v152
	v_fmac_f32_e32 v202, v225, v71
	v_lshlrev_b32_e32 v71, 16, v153
	v_fmac_f32_e32 v202, v226, v71
	v_and_b32_e32 v71, 0xffff0000, v153
	v_fmac_f32_e32 v202, v227, v71
	s_waitcnt lgkmcnt(1)
	v_lshlrev_b32_e32 v71, 16, v146
	v_fmac_f32_e32 v202, v228, v71
	v_and_b32_e32 v71, 0xffff0000, v146
	v_fmac_f32_e32 v202, v229, v71
	v_lshlrev_b32_e32 v71, 16, v147
	v_fmac_f32_e32 v202, v230, v71
	v_and_b32_e32 v71, 0xffff0000, v147
	v_fmac_f32_e32 v202, v231, v71
	s_waitcnt lgkmcnt(0)
	v_lshlrev_b32_e32 v71, 16, v148
	v_fmac_f32_e32 v202, v232, v71
	v_and_b32_e32 v71, 0xffff0000, v148
	v_fmac_f32_e32 v202, v233, v71
	v_lshlrev_b32_e32 v71, 16, v149
	v_fmac_f32_e32 v202, v234, v71
	v_and_b32_e32 v71, 0xffff0000, v149
	v_fmac_f32_e32 v202, v235, v71
	v_mfma_f32_32x32x16_bf16 v[66:81], v[174:177], v[66:69], 0
	v_mov_b32_e32 v205, v202
	s_nop 1
	v_permlane32_swap_b32_e32 v202, v205
	v_mfma_f32_32x32x16_bf16 v[66:81], v[170:173], v[106:109], v[66:81]
	v_mfma_f32_32x32x16_bf16 v[66:81], v[166:169], v[102:105], v[66:81]
	v_mfma_f32_32x32x16_bf16 v[66:81], v[162:165], v[98:101], v[66:81]
	v_mfma_f32_32x32x16_bf16 v[66:81], v[158:161], v[94:97], v[66:81]
	v_mfma_f32_32x32x16_bf16 v[66:81], v[154:157], v[90:93], v[66:81]
	v_mfma_f32_32x32x16_bf16 v[66:81], v[150:153], v[82:85], v[66:81]
	v_add_u32_e32 v82, 0x20400, v206
	ds_read_b32 v82, v82
	s_waitcnt lgkmcnt(0)
	v_max_f32_e32 v82, v82, v82
	v_mfma_f32_32x32x16_bf16 v[66:81], v[146:149], v[86:89], v[66:81]
	v_max_f32_e32 v210, v112, v82
	v_sub_f32_e32 v82, v193, v210
	v_mul_f32_e32 v82, 0x3fb8aa3b, v82
	v_exp_f32_e32 v209, v82
	s_and_saveexec_b64 s[22:23], s[8:9]
	ds_write_b32 v207, v209
	s_or_b64 exec, exec, s[22:23]
	v_lshlrev_b32_e32 v83, 4, v111
	v_lshlrev_b32_e32 v82, 3, v111
	v_and_b32_e32 v83, 0xc0, v83
	v_and_or_b32 v98, v82, 24, v83
	v_lshlrev_b32_e32 v83, 1, v111
	s_waitcnt lgkmcnt(0)
	v_add_u32_e32 v94, s38, v0
	v_and_b32_e32 v99, 32, v83
	v_and_b32_e32 v100, 0x100, v82
	ds_read_b128 v[82:85], v94 offset:64
	ds_read_b128 v[86:89], v94 offset:96
	ds_read_b128 v[90:93], v94
	ds_read_b128 v[94:97], v94 offset:32
	v_or3_b32 v204, v98, v99, v100
	s_waitcnt lgkmcnt(3)
	v_pk_mul_f32 v[58:59], v[58:59], v[82:83]
	v_pk_mul_f32 v[74:75], v[74:75], v[82:83]
	v_lshlrev_b32_e32 v82, 4, v191
	s_waitcnt lgkmcnt(2)
	v_pk_mul_f32 v[62:63], v[62:63], v[86:87]
	v_pk_mul_f32 v[64:65], v[64:65], v[88:89]
	v_pk_mul_f32 v[60:61], v[60:61], v[84:85]
	v_pk_mul_f32 v[78:79], v[78:79], v[86:87]
	v_pk_mul_f32 v[80:81], v[80:81], v[88:89]
	v_pk_mul_f32 v[76:77], v[76:77], v[84:85]
	v_bitop3_b32 v83, v0, v82, s43 bitop3:0x78
	v_bitop3_b32 v84, v180, v82, s43 bitop3:0x78
	v_bitop3_b32 v85, v181, v82, s43 bitop3:0x78
	v_bitop3_b32 v86, v211, v82, s43 bitop3:0x78
	v_bitop3_b32 v87, v213, v82, s43 bitop3:0x78
	v_bitop3_b32 v88, v214, v82, s43 bitop3:0x78
	v_bitop3_b32 v89, v215, v82, s43 bitop3:0x78
	v_bitop3_b32 v82, v216, v82, s43 bitop3:0x78
	v_add_u32_e32 v203, s56, v204
	s_waitcnt lgkmcnt(0)
	v_pk_mul_f32 v[54:55], v[54:55], v[94:95]
	v_pk_mul_f32 v[56:57], v[56:57], v[96:97]
	v_pk_mul_f32 v[52:53], v[52:53], v[92:93]
	v_pk_mul_f32 v[50:51], v[50:51], v[90:91]
	v_pk_mul_f32 v[70:71], v[70:71], v[94:95]
	v_pk_mul_f32 v[72:73], v[72:73], v[96:97]
	v_pk_mul_f32 v[68:69], v[68:69], v[92:93]
	v_pk_mul_f32 v[66:67], v[66:67], v[90:91]
	v_mul_f32_e32 v212, 0x3fb8aa3b, v210
	v_lshlrev_b32_e32 v211, 2, v110
	s_andn2_b64 vcc, exec, s[94:95]
	v_add3_u32 v220, 0, v83, v113
	v_add3_u32 v219, 0, v84, v113
	v_add3_u32 v218, 0, v85, v113
	v_add3_u32 v217, 0, v86, v113
	v_add3_u32 v216, 0, v87, v113
	v_add3_u32 v215, 0, v88, v113
	v_add3_u32 v214, 0, v89, v113
	v_add3_u32 v213, 0, v82, v113
	s_cbranch_vccnz .LBB0_235
; __device__ __forceinline__ int crow(int r, int hi) { return (r & 3) + 8 * (r >> 2) + 4 * hi; }
; __device__ __forceinline__ void mlstm_item(const int tid0, const P& p, int item, char* lds) {
;     ...
;             qkt(p0, p1, Ks + kt * 16384, qr, r32, hi);
; #pragma unroll
;             for (int r = 0; r < 16; ++r) {
;                 const int s0 = 64 * kt + crow(r, hi), s1 = s0 + 32;
;                 const bool a0 = dir ? (s0 >= tl) : (s0 <= tl), a1 = dir ? (s1 >= tl) : (s1 <= tl);
;                 const float w0 = a0 ? __builtin_amdgcn_exp2f(fminf(su[s0] * 1.4426950408889634f - MtL, 0.f)) : 0.f;
;                 const float w1 = a1 ? __builtin_amdgcn_exp2f(fminf(su[s1] * 1.4426950408889634f - MtL, 0.f)) : 0.f;
	ds_read_b128 v[82:85], v220
	ds_read_b128 v[86:89], v220 offset:8192
	ds_read_b128 v[222:225], v219
	ds_read_b128 v[226:229], v219 offset:8192
	v_cmp_le_u32_e32 vcc, v211, v201
	v_mov_b32_e32 v221, 0
	s_waitcnt lgkmcnt(3)
	v_mfma_f32_32x32x16_bf16 v[98:113], v[82:85], v[174:177], 0
	v_cndmask_b32_e64 v180, 0, 1, vcc
	v_cmp_ge_u32_e32 vcc, v211, v201
	s_nop 1
	v_cndmask_b32_e64 v181, 0, 1, vcc
	v_cndmask_b32_e64 v180, v181, v180, s[4:5]
	v_and_b32_e32 v180, 1, v180
	s_waitcnt lgkmcnt(2)
	v_mfma_f32_32x32x16_bf16 v[82:97], v[86:89], v[174:177], 0
	v_cmp_eq_u32_e32 vcc, 1, v180
	s_waitcnt lgkmcnt(1)
	v_mfma_f32_32x32x16_bf16 v[98:113], v[222:225], v[170:173], v[98:113]
	s_waitcnt lgkmcnt(0)
	v_mfma_f32_32x32x16_bf16 v[82:97], v[226:229], v[170:173], v[82:97]
	ds_read_b128 v[222:225], v218
	ds_read_b128 v[226:229], v218 offset:8192
	s_waitcnt lgkmcnt(1)
	v_mfma_f32_32x32x16_bf16 v[98:113], v[222:225], v[166:169], v[98:113]
	s_waitcnt lgkmcnt(0)
	v_mfma_f32_32x32x16_bf16 v[82:97], v[226:229], v[166:169], v[82:97]
	ds_read_b128 v[222:225], v217
	ds_read_b128 v[226:229], v217 offset:8192
	s_waitcnt lgkmcnt(1)
	v_mfma_f32_32x32x16_bf16 v[98:113], v[222:225], v[162:165], v[98:113]
	s_waitcnt lgkmcnt(0)
	v_mfma_f32_32x32x16_bf16 v[82:97], v[226:229], v[162:165], v[82:97]
	ds_read_b128 v[222:225], v216
	ds_read_b128 v[226:229], v216 offset:8192
	s_waitcnt lgkmcnt(1)
	v_mfma_f32_32x32x16_bf16 v[98:113], v[222:225], v[158:161], v[98:113]
	s_waitcnt lgkmcnt(0)
	v_mfma_f32_32x32x16_bf16 v[82:97], v[226:229], v[158:161], v[82:97]
	ds_read_b128 v[222:225], v215
	ds_read_b128 v[226:229], v215 offset:8192
	s_waitcnt lgkmcnt(1)
	v_mfma_f32_32x32x16_bf16 v[98:113], v[222:225], v[154:157], v[98:113]
	s_waitcnt lgkmcnt(0)
	v_mfma_f32_32x32x16_bf16 v[82:97], v[226:229], v[154:157], v[82:97]
	ds_read_b128 v[222:225], v214
	ds_read_b128 v[226:229], v214 offset:8192
	s_waitcnt lgkmcnt(1)
	v_mfma_f32_32x32x16_bf16 v[98:113], v[222:225], v[150:153], v[98:113]
	s_waitcnt lgkmcnt(0)
	v_mfma_f32_32x32x16_bf16 v[82:97], v[226:229], v[150:153], v[82:97]
	ds_read_b128 v[222:225], v213
	ds_read_b128 v[226:229], v213 offset:8192
	s_waitcnt lgkmcnt(1)
	v_mfma_f32_32x32x16_bf16 v[98:113], v[222:225], v[146:149], v[98:113]
	v_mov_b32_e32 v222, 0
	s_waitcnt lgkmcnt(0)
	v_mfma_f32_32x32x16_bf16 v[82:97], v[226:229], v[146:149], v[82:97]
	v_lshl_add_u32 v241, v211, 2, 0
	v_add_u32_e32 v241, 0x20200, v241
	ds_read_b32 v222, v241 offset:0
	ds_read_b32 v223, v241 offset:128
	ds_read_b32 v221, v241 offset:4
	ds_read_b32 v225, v241 offset:132
	ds_read_b32 v224, v241 offset:8
	ds_read_b32 v227, v241 offset:136
	ds_read_b32 v226, v241 offset:12
	ds_read_b32 v229, v241 offset:140
	ds_read_b32 v228, v241 offset:32
	ds_read_b32 v231, v241 offset:160
	ds_read_b32 v230, v241 offset:36
	ds_read_b32 v233, v241 offset:164
	ds_read_b32 v232, v241 offset:40
	ds_read_b32 v235, v241 offset:168
	ds_read_b32 v234, v241 offset:44
	ds_read_b32 v237, v241 offset:172
	ds_read_b32 v236, v241 offset:64
	ds_read_b32 v239, v241 offset:192
	ds_read_b32 v238, v241 offset:68
	ds_read_b32 v246, v241 offset:196
	ds_read_b32 v245, v241 offset:72
	ds_read_b32 v248, v241 offset:200
	ds_read_b32 v247, v241 offset:76
	ds_read_b32 v250, v241 offset:204
	ds_read_b32 v249, v241 offset:96
	ds_read_b32 v252, v241 offset:224
	ds_read_b32 v251, v241 offset:100
	ds_read_b32 v243, v241 offset:228
	ds_read_b32 v253, v241 offset:104
	ds_read_b32 v240, v241 offset:232
	ds_read_b32 v180, v241 offset:108
	ds_read_b32 v181, v241 offset:236
	v_sub_u32_e32 v179, v201, v211
	s_waitcnt lgkmcnt(0)
	s_cmp_lg_u64 s[4:5], 0
	s_cbranch_scc0 .Lmlw_d1_k0
; __device__ __forceinline__ int crow(int r, int hi) { return (r & 3) + 8 * (r >> 2) + 4 * hi; }
; __device__ __forceinline__ void mlstm_item(const int tid0, const P& p, int item, char* lds) {
;     ...
;             for (int r = 0; r < 16; ++r) {
;                 const int s0 = 64 * kt + crow(r, hi), s1 = s0 + 32;
;                 const bool a0 = dir ? (s0 >= tl) : (s0 <= tl), a1 = dir ? (s1 >= tl) : (s1 <= tl);
;                 const float w0 = a0 ? __builtin_amdgcn_exp2f(fminf(su[s0] * 1.4426950408889634f - MtL, 0.f)) : 0.f;
;                 const float w1 = a1 ? __builtin_amdgcn_exp2f(fminf(su[s1] * 1.4426950408889634f - MtL, 0.f)) : 0.f;
;                 p0[r] *= w0; p1[r] *= w1; dsum += p0[r] + p1[r];
	v_fma_f32 v222, v222, s41, -v212
	v_min_f32_e32 v222, 0, v222
	v_exp_f32_e32 v222, v222
	v_cmp_le_i32_e32 vcc, 0, v179
	v_fma_f32 v223, v223, s41, -v212
	v_min_f32_e32 v223, 0, v223
	v_exp_f32_e32 v223, v223
	v_cmp_le_i32_e64 s[22:23], 32, v179
	v_cndmask_b32_e32 v222, 0, v222, vcc
	v_fma_f32 v221, v221, s41, -v212
	v_min_f32_e32 v221, 0, v221
	v_exp_f32_e32 v221, v221
	v_cmp_le_i32_e32 vcc, 1, v179
	v_cndmask_b32_e64 v223, 0, v223, s[22:23]
	v_fma_f32 v225, v225, s41, -v212
	v_min_f32_e32 v225, 0, v225
	v_exp_f32_e32 v225, v225
	v_cmp_le_i32_e64 s[22:23], 33, v179
	v_cndmask_b32_e32 v221, 0, v221, vcc
	v_fma_f32 v224, v224, s41, -v212
	v_min_f32_e32 v224, 0, v224
	v_exp_f32_e32 v224, v224
	v_cmp_le_i32_e32 vcc, 2, v179
	v_cndmask_b32_e64 v225, 0, v225, s[22:23]
	v_fma_f32 v227, v227, s41, -v212
	v_min_f32_e32 v227, 0, v227
	v_exp_f32_e32 v227, v227
	v_cmp_le_i32_e64 s[22:23], 34, v179
	v_cndmask_b32_e32 v224, 0, v224, vcc
	v_fma_f32 v226, v226, s41, -v212
	v_min_f32_e32 v226, 0, v226
	v_exp_f32_e32 v226, v226
	v_cmp_le_i32_e32 vcc, 3, v179
	v_cndmask_b32_e64 v227, 0, v227, s[22:23]
	v_fma_f32 v229, v229, s41, -v212
	v_min_f32_e32 v229, 0, v229
	v_exp_f32_e32 v229, v229
	v_cmp_le_i32_e64 s[22:23], 35, v179
	v_cndmask_b32_e32 v226, 0, v226, vcc
	v_fma_f32 v228, v228, s41, -v212
	v_min_f32_e32 v228, 0, v228
	v_exp_f32_e32 v228, v228
	v_cmp_le_i32_e32 vcc, 8, v179
	v_cndmask_b32_e64 v229, 0, v229, s[22:23]
	v_fma_f32 v231, v231, s41, -v212
	v_min_f32_e32 v231, 0, v231
	v_exp_f32_e32 v231, v231
	v_cmp_le_i32_e64 s[22:23], 40, v179
	v_cndmask_b32_e32 v228, 0, v228, vcc
	v_fma_f32 v230, v230, s41, -v212
	v_min_f32_e32 v230, 0, v230
	v_exp_f32_e32 v230, v230
	v_cmp_le_i32_e32 vcc, 9, v179
	v_cndmask_b32_e64 v231, 0, v231, s[22:23]
	v_fma_f32 v233, v233, s41, -v212
	v_min_f32_e32 v233, 0, v233
	v_exp_f32_e32 v233, v233
	v_cmp_le_i32_e64 s[22:23], 41, v179
	v_cndmask_b32_e32 v230, 0, v230, vcc
	v_fma_f32 v232, v232, s41, -v212
	v_min_f32_e32 v232, 0, v232
	v_exp_f32_e32 v232, v232
	v_cmp_le_i32_e32 vcc, 10, v179
	v_cndmask_b32_e64 v233, 0, v233, s[22:23]
	v_fma_f32 v235, v235, s41, -v212
	v_min_f32_e32 v235, 0, v235
	v_exp_f32_e32 v235, v235
	v_cmp_le_i32_e64 s[22:23], 42, v179
	v_cndmask_b32_e32 v232, 0, v232, vcc
	v_fma_f32 v234, v234, s41, -v212
	v_min_f32_e32 v234, 0, v234
	v_exp_f32_e32 v234, v234
	v_cmp_le_i32_e32 vcc, 11, v179
	v_cndmask_b32_e64 v235, 0, v235, s[22:23]
	v_fma_f32 v237, v237, s41, -v212
	v_min_f32_e32 v237, 0, v237
	v_exp_f32_e32 v237, v237
	v_cmp_le_i32_e64 s[22:23], 43, v179
	v_cndmask_b32_e32 v234, 0, v234, vcc
	v_fma_f32 v236, v236, s41, -v212
	v_min_f32_e32 v236, 0, v236
	v_exp_f32_e32 v236, v236
	v_cmp_le_i32_e32 vcc, 16, v179
	v_cndmask_b32_e64 v237, 0, v237, s[22:23]
	v_fma_f32 v239, v239, s41, -v212
	v_min_f32_e32 v239, 0, v239
	v_exp_f32_e32 v239, v239
	v_cmp_le_i32_e64 s[22:23], 48, v179
	v_cndmask_b32_e32 v236, 0, v236, vcc
	v_fma_f32 v238, v238, s41, -v212
	v_min_f32_e32 v238, 0, v238
	v_exp_f32_e32 v238, v238
	v_cmp_le_i32_e32 vcc, 17, v179
	v_cndmask_b32_e64 v239, 0, v239, s[22:23]
	v_fma_f32 v246, v246, s41, -v212
	v_min_f32_e32 v246, 0, v246
	v_exp_f32_e32 v246, v246
	v_cmp_le_i32_e64 s[22:23], 49, v179
	v_cndmask_b32_e32 v238, 0, v238, vcc
	v_fma_f32 v245, v245, s41, -v212
	v_min_f32_e32 v245, 0, v245
	v_exp_f32_e32 v245, v245
	v_cmp_le_i32_e32 vcc, 18, v179
	v_cndmask_b32_e64 v246, 0, v246, s[22:23]
	v_fma_f32 v248, v248, s41, -v212
	v_min_f32_e32 v248, 0, v248
	v_exp_f32_e32 v248, v248
	v_cmp_le_i32_e64 s[22:23], 50, v179
	v_cndmask_b32_e32 v245, 0, v245, vcc
	v_fma_f32 v247, v247, s41, -v212
	v_min_f32_e32 v247, 0, v247
	v_exp_f32_e32 v247, v247
	v_cmp_le_i32_e32 vcc, 19, v179
	v_cndmask_b32_e64 v248, 0, v248, s[22:23]
	v_fma_f32 v250, v250, s41, -v212
	v_min_f32_e32 v250, 0, v250
	v_exp_f32_e32 v250, v250
	v_cmp_le_i32_e64 s[22:23], 51, v179
	v_cndmask_b32_e32 v247, 0, v247, vcc
	v_fma_f32 v249, v249, s41, -v212
	v_min_f32_e32 v249, 0, v249
	v_exp_f32_e32 v249, v249
	v_cmp_le_i32_e32 vcc, 24, v179
	v_cndmask_b32_e64 v250, 0, v250, s[22:23]
	v_fma_f32 v252, v252, s41, -v212
	v_min_f32_e32 v252, 0, v252
	v_exp_f32_e32 v252, v252
	v_cmp_le_i32_e64 s[22:23], 56, v179
	v_cndmask_b32_e32 v249, 0, v249, vcc
	v_fma_f32 v251, v251, s41, -v212
	v_min_f32_e32 v251, 0, v251
	v_exp_f32_e32 v251, v251
	v_cmp_le_i32_e32 vcc, 25, v179
	v_cndmask_b32_e64 v252, 0, v252, s[22:23]
	v_fma_f32 v243, v243, s41, -v212
	v_min_f32_e32 v243, 0, v243
	v_exp_f32_e32 v243, v243
	v_cmp_le_i32_e64 s[22:23], 57, v179
	v_cndmask_b32_e32 v251, 0, v251, vcc
	v_fma_f32 v253, v253, s41, -v212
	v_min_f32_e32 v253, 0, v253
	v_exp_f32_e32 v253, v253
	v_cmp_le_i32_e32 vcc, 26, v179
	v_cndmask_b32_e64 v243, 0, v243, s[22:23]
	v_fma_f32 v240, v240, s41, -v212
	v_min_f32_e32 v240, 0, v240
	v_exp_f32_e32 v240, v240
	v_cmp_le_i32_e64 s[22:23], 58, v179
	v_cndmask_b32_e32 v253, 0, v253, vcc
	v_fma_f32 v180, v180, s41, -v212
	v_min_f32_e32 v180, 0, v180
	v_exp_f32_e32 v180, v180
	v_cmp_le_i32_e32 vcc, 27, v179
	v_cndmask_b32_e64 v240, 0, v240, s[22:23]
	v_fma_f32 v181, v181, s41, -v212
	v_min_f32_e32 v181, 0, v181
	v_exp_f32_e32 v181, v181
	v_cmp_le_i32_e64 s[22:23], 59, v179
	v_cndmask_b32_e32 v180, 0, v180, vcc
	s_nop 1
	v_cndmask_b32_e64 v181, 0, v181, s[22:23]
	s_branch .Lmlw_done_k0

; __device__ __forceinline__ unsigned cvtpk(float lo, float hi) { unsigned r; asm volatile("v_cvt_pk_bf16_f32 %0, %1, %2" : "=v"(r) : "v"(lo), "v"(hi)); return r; }
; __device__ __forceinline__ int crow(int r, int hi) { return (r & 3) + 8 * (r >> 2) + 4 * hi; }
; __device__ __forceinline__ void mlstm_item(const int tid0, const P& p, int item, char* lds) {
;     ...
;         if (hi == 0) wsr[32 + r32] = rsc;
;         asm volatile("s_waitcnt lgkmcnt(0)" ::: "memory");
; #pragma unroll
;         for (int r = 0; r < 16; ++r) { const int rr = crow(r, hi); const float f = wsr[32 + rr];
;             bf16_t* hp = Hg + (size_t)(t0 + 32 * w4 + rr) * ZLD + 64 * vh + r32;
;             hp[0] = (bf16_t)(cvtpk(o0[r] * f, 0.f) & 0xffffu); hp[32] = (bf16_t)(cvtpk(o1[r] * f, 0.f) & 0xffffu); }
.LBB0_303:
	s_or_b64 exec, exec, s[22:23]
	s_waitcnt lgkmcnt(0)
	v_lshl_add_u32 v86, v211, 2, s38
	ds_read_b128 v[116:119], v86 offset:128
	ds_read_b128 v[120:123], v86 offset:160
	ds_read_b128 v[124:127], v86 offset:192
	ds_read_b128 v[128:131], v86 offset:224
	s_add_i32 s21, s21, s17
	v_lshlrev_b32_e32 v82, 1, v191
	v_mov_b32_e32 v83, v1
	v_lshl_add_u64 v[82:83], s[24:25], 0, v[82:83]
	v_add_u32_e32 v88, s21, v211
	s_waitcnt lgkmcnt(0)
	v_mul_f32_e32 v50, v50, v116
	v_mad_i64_i32 v[84:85], s[8:9], v88, s44, v[82:83]
	v_cvt_pk_bf16_f32 v50, v50, v1
	global_store_short v[84:85], v50, off
	v_mul_f32_e32 v50, v66, v116
	v_cvt_pk_bf16_f32 v50, v50, v1
	global_store_short v[84:85], v50, off offset:64
	v_add_u32_e32 v50, 1, v88
	v_mad_i64_i32 v[84:85], s[8:9], v50, s44, v[82:83]
	v_mul_f32_e32 v50, v51, v117
	v_cvt_pk_bf16_f32 v50, v50, v1
	global_store_short v[84:85], v50, off
	v_mul_f32_e32 v50, v67, v117
	v_cvt_pk_bf16_f32 v50, v50, v1
	global_store_short v[84:85], v50, off offset:64
	v_add_u32_e32 v50, 2, v88
	v_mad_i64_i32 v[50:51], s[8:9], v50, s44, v[82:83]
	v_mul_f32_e32 v52, v52, v118
	v_cvt_pk_bf16_f32 v52, v52, v1
	global_store_short v[50:51], v52, off
	v_mul_f32_e32 v52, v68, v118
	v_cvt_pk_bf16_f32 v52, v52, v1
	global_store_short v[50:51], v52, off offset:64
	v_add_u32_e32 v50, 3, v88
	v_mad_i64_i32 v[50:51], s[8:9], v50, s44, v[82:83]
	v_mul_f32_e32 v52, v53, v119
	v_cvt_pk_bf16_f32 v52, v52, v1
	global_store_short v[50:51], v52, off
	v_mul_f32_e32 v52, v69, v119
	v_cvt_pk_bf16_f32 v52, v52, v1
	global_store_short v[50:51], v52, off offset:64
	v_add_u32_e32 v50, 8, v88
	v_mad_i64_i32 v[50:51], s[8:9], v50, s44, v[82:83]
	v_mul_f32_e32 v52, v54, v120
	v_cvt_pk_bf16_f32 v52, v52, v1
	global_store_short v[50:51], v52, off
	v_mul_f32_e32 v52, v70, v120
	v_cvt_pk_bf16_f32 v52, v52, v1
	global_store_short v[50:51], v52, off offset:64
	v_add_u32_e32 v50, 9, v88
	v_mad_i64_i32 v[50:51], s[8:9], v50, s44, v[82:83]
	v_mul_f32_e32 v52, v55, v121
	v_cvt_pk_bf16_f32 v52, v52, v1
	global_store_short v[50:51], v52, off
	v_mul_f32_e32 v52, v71, v121
	v_cvt_pk_bf16_f32 v52, v52, v1
	global_store_short v[50:51], v52, off offset:64
	v_add_u32_e32 v50, 10, v88
	v_mad_i64_i32 v[50:51], s[8:9], v50, s44, v[82:83]
	v_mul_f32_e32 v52, v56, v122
	v_cvt_pk_bf16_f32 v52, v52, v1
	global_store_short v[50:51], v52, off
	v_mul_f32_e32 v52, v72, v122
	v_cvt_pk_bf16_f32 v52, v52, v1
	global_store_short v[50:51], v52, off offset:64
	v_add_u32_e32 v50, 11, v88
	v_mad_i64_i32 v[50:51], s[8:9], v50, s44, v[82:83]
	v_mul_f32_e32 v52, v57, v123
	v_cvt_pk_bf16_f32 v52, v52, v1
	global_store_short v[50:51], v52, off
	v_mul_f32_e32 v52, v73, v123
	v_cvt_pk_bf16_f32 v52, v52, v1
	global_store_short v[50:51], v52, off offset:64
	v_add_u32_e32 v50, 16, v88
	v_mad_i64_i32 v[50:51], s[8:9], v50, s44, v[82:83]
	v_mul_f32_e32 v52, v58, v124
	v_cvt_pk_bf16_f32 v52, v52, v1
	global_store_short v[50:51], v52, off
	v_mul_f32_e32 v52, v74, v124
	v_cvt_pk_bf16_f32 v52, v52, v1
	global_store_short v[50:51], v52, off offset:64
	v_add_u32_e32 v50, 17, v88
	v_mad_i64_i32 v[50:51], s[8:9], v50, s44, v[82:83]
	v_mul_f32_e32 v52, v59, v125
	v_cvt_pk_bf16_f32 v52, v52, v1
	global_store_short v[50:51], v52, off
	v_mul_f32_e32 v52, v75, v125
	v_cvt_pk_bf16_f32 v52, v52, v1
	global_store_short v[50:51], v52, off offset:64
	v_add_u32_e32 v50, 18, v88
	v_mad_i64_i32 v[50:51], s[8:9], v50, s44, v[82:83]
	v_mul_f32_e32 v52, v60, v126
	v_cvt_pk_bf16_f32 v52, v52, v1
	global_store_short v[50:51], v52, off
	v_mul_f32_e32 v52, v76, v126
	v_cvt_pk_bf16_f32 v52, v52, v1
	global_store_short v[50:51], v52, off offset:64
	v_add_u32_e32 v50, 19, v88
	v_mad_i64_i32 v[50:51], s[8:9], v50, s44, v[82:83]
	v_mul_f32_e32 v52, v61, v127
	v_cvt_pk_bf16_f32 v52, v52, v1
	global_store_short v[50:51], v52, off
	v_mul_f32_e32 v52, v77, v127
	v_cvt_pk_bf16_f32 v52, v52, v1
	global_store_short v[50:51], v52, off offset:64
	v_add_u32_e32 v50, 24, v88
	v_mad_i64_i32 v[50:51], s[8:9], v50, s44, v[82:83]
	v_mul_f32_e32 v52, v62, v128
	v_cvt_pk_bf16_f32 v52, v52, v1
	global_store_short v[50:51], v52, off
	v_mul_f32_e32 v52, v78, v128
	v_cvt_pk_bf16_f32 v52, v52, v1
	global_store_short v[50:51], v52, off offset:64
	v_add_u32_e32 v50, 25, v88
	v_mad_i64_i32 v[50:51], s[8:9], v50, s44, v[82:83]
	v_mul_f32_e32 v52, v63, v129
	v_cvt_pk_bf16_f32 v52, v52, v1
	global_store_short v[50:51], v52, off
	v_mul_f32_e32 v52, v79, v129
	v_cvt_pk_bf16_f32 v52, v52, v1
	global_store_short v[50:51], v52, off offset:64
	v_add_u32_e32 v50, 26, v88
	v_mad_i64_i32 v[50:51], s[8:9], v50, s44, v[82:83]
	v_mul_f32_e32 v52, v64, v130
	v_cvt_pk_bf16_f32 v52, v52, v1
	global_store_short v[50:51], v52, off
	v_mul_f32_e32 v52, v80, v130
	v_cvt_pk_bf16_f32 v52, v52, v1
	global_store_short v[50:51], v52, off offset:64
	v_add_u32_e32 v50, 27, v88
	v_mad_i64_i32 v[50:51], s[8:9], v50, s44, v[82:83]
	v_mul_f32_e32 v52, v65, v131
	v_cvt_pk_bf16_f32 v52, v52, v1
	global_store_short v[50:51], v52, off
	v_mul_f32_e32 v52, v81, v131
	s_cmp_eq_u32 s28, -1
	v_cvt_pk_bf16_f32 v52, v52, v1
	global_store_short v[50:51], v52, off offset:64
	s_cbranch_scc1 .LBB0_307
	s_and_b64 s[8:9], s[4:5], exec
	s_cselect_b32 s8, s30, s28
	s_lshl_b32 s21, s8, 7
	v_mov_b32_e32 v179, v1
	v_add_u32_e32 v54, s21, v197
	v_ashrrev_i32_e32 v55, 31, v54
	v_lshl_add_u64 v[50:51], s[60:61], 0, v[178:179]
	v_lshlrev_b64 v[56:57], 12, v[54:55]
	v_lshl_add_u64 v[52:53], s[46:47], 0, v[178:179]
	v_lshl_add_u64 v[56:57], v[50:51], 0, v[56:57]
	global_load_dwordx4 v[114:117], v[56:57], off offset:2048
	v_mad_i64_i32 v[56:57], s[8:9], v54, s44, v[52:53]
	global_load_dwordx4 v[118:121], v[56:57], off
	v_add_u32_e32 v56, s21, v198
	v_ashrrev_i32_e32 v57, 31, v56
	v_lshl_add_u64 v[54:55], v[54:55], 2, s[0:1]
	v_lshlrev_b64 v[58:59], 12, v[56:57]
	v_lshl_add_u64 v[58:59], v[50:51], 0, v[58:59]
	global_load_dword v179, v[54:55], off
	global_load_dwordx4 v[122:125], v[58:59], off offset:2048
	v_mad_i64_i32 v[54:55], s[8:9], v56, s44, v[52:53]
	global_load_dwordx4 v[126:129], v[54:55], off
	v_lshl_add_u64 v[54:55], v[56:57], 2, s[0:1]
	v_add_u32_e32 v56, s21, v199
	v_ashrrev_i32_e32 v57, 31, v56
	v_lshlrev_b64 v[58:59], 12, v[56:57]
	v_lshl_add_u64 v[58:59], v[50:51], 0, v[58:59]
	global_load_dword v182, v[54:55], off
	global_load_dwordx4 v[130:133], v[58:59], off offset:2048
	v_mad_i64_i32 v[54:55], s[8:9], v56, s44, v[52:53]
	global_load_dwordx4 v[134:137], v[54:55], off
	v_lshl_add_u64 v[54:55], v[56:57], 2, s[0:1]
	v_add_u32_e32 v56, s21, v200
	v_ashrrev_i32_e32 v57, 31, v56
	v_lshlrev_b64 v[58:59], 12, v[56:57]
	v_lshl_add_u64 v[50:51], v[50:51], 0, v[58:59]
	global_load_dword v186, v[54:55], off
	global_load_dwordx4 v[138:141], v[50:51], off offset:2048
	v_mad_i64_i32 v[50:51], s[8:9], v56, s44, v[52:53]
	global_load_dwordx4 v[142:145], v[50:51], off
	v_lshl_add_u64 v[50:51], v[56:57], 2, s[0:1]
	global_load_dword v187, v[50:51], off
	s_and_saveexec_b64 s[8:9], s[6:7]
	s_cbranch_execz .LBB0_306
	v_add_u32_e32 v50, s21, v196
	v_ashrrev_i32_e32 v51, 31, v50
	v_lshlrev_b64 v[50:51], 2, v[50:51]
	v_lshl_add_u64 v[52:53], s[68:69], 0, v[50:51]
	v_lshl_add_u64 v[54:55], s[0:1], 0, v[50:51]
	v_lshl_add_u64 v[50:51], s[58:59], 0, v[50:51]
	global_load_dword v183, v[50:51], off
	global_load_dword v184, v[54:55], off
	global_load_dword v185, v[52:53], off
